# deferred seams: XCD leader releases its local workgroups before posting the cross-XCD arrival
# speedup vs baseline: 1.0043x; 1.0043x over previous
; __device__ __forceinline__ unsigned xb_ld(unsigned* p)              { return __hip_atomic_load(p, __ATOMIC_RELAXED, __HIP_MEMORY_SCOPE_AGENT); }
; __device__ __forceinline__ unsigned xb_add(unsigned* p, unsigned v) { return __hip_atomic_fetch_add(p, v, __ATOMIC_RELAXED, __HIP_MEMORY_SCOPE_AGENT); }
; #define XB_SPIN(cond, bar) do { unsigned _sp = 0; while (cond) { __builtin_amdgcn_s_sleep(1); \
;     if ((++_sp & 255u) == 0u) { if (xb_ld(&(bar)[XB_TMO])) break; if (_sp > XB_SPIN_CAP) { atomicAdd(&(bar)[XB_TMO], 1u); break; } } } } while (0)
; __device__ __forceinline__ void xcd_barrier(const XcdBarrier& b) {
;     ...
;         const unsigned old = xb_add(&bar[XB_XSUB(b.x)], 1u);
;         const unsigned gen = old / nloc;
;         if (old + 1u == (gen + 1u) * nloc) {
;             __builtin_amdgcn_fence(__ATOMIC_RELEASE, "agent");
;             asm volatile("s_waitcnt vmcnt(0)" ::: "memory");
;             const unsigned og = xb_add(&bar[XB_TOP], 1u);
;             const unsigned tg = og / nx;
;             if (og + 1u == (tg + 1u) * nx) xb_add(&bar[XB_TOPGEN], 1u);
;             else XB_SPIN(xb_ld(&bar[XB_TOPGEN]) == tg, bar);
;             __builtin_amdgcn_fence(__ATOMIC_ACQUIRE, "agent");
;             xb_add(&bar[XB_XGEN(b.x)], 1u);
.LBB0_365:
	s_andn2_saveexec_b64 s[8:9], s[8:9]
	s_cbranch_execz .LBB0_385
	s_mov_b64 s[8:9], exec
	v_readlane_b32 s101, v249, 48
	s_nop 3
	s_cmp_lg_u32 s101, 0
	s_cbranch_scc1 .Lrel_0
	buffer_wbl2 sc1
	s_branch .Lnowb_0
.Lrel_0:
	v_mov_b32_e32 v250, 0x2000
	v_mov_b32_e32 v251, 1
	global_atomic_add v250, v251, s[6:7] offset:1024

; __device__ __forceinline__ unsigned xb_ld(unsigned* p)              { return __hip_atomic_load(p, __ATOMIC_RELAXED, __HIP_MEMORY_SCOPE_AGENT); }
; __device__ __forceinline__ unsigned xb_add(unsigned* p, unsigned v) { return __hip_atomic_fetch_add(p, v, __ATOMIC_RELAXED, __HIP_MEMORY_SCOPE_AGENT); }
; #define XB_SPIN(cond, bar) do { unsigned _sp = 0; while (cond) { __builtin_amdgcn_s_sleep(1); \
;     if ((++_sp & 255u) == 0u) { if (xb_ld(&(bar)[XB_TMO])) break; if (_sp > XB_SPIN_CAP) { atomicAdd(&(bar)[XB_TMO], 1u); break; } } } } while (0)
; __device__ __forceinline__ void xcd_barrier(const XcdBarrier& b) {
;     ...
;             xb_add(&bar[XB_XGEN(b.x)], 1u);
;             asm volatile("s_waitcnt vmcnt(0)" ::: "memory");
;         } else {
;             XB_SPIN(xb_ld(&bar[XB_XGEN(b.x)]) == gen, bar);
;             __builtin_amdgcn_fence(__ATOMIC_ACQUIRE, "agent");
;             asm volatile("s_waitcnt vmcnt(0)" ::: "memory");
;         }
;     }
;     __syncthreads();
.LBB0_382:
	s_or_b64 exec, exec, s[8:9]
	s_mov_b64 s[8:9], exec
	v_mbcnt_lo_u32_b32 v0, s8, 0
	v_mbcnt_hi_u32_b32 v0, s9, v0
	v_cmp_eq_u32_e32 vcc, 0, v0
	s_waitcnt vmcnt(0)
	v_readlane_b32 s101, v249, 48
	s_nop 3
	s_cmp_lg_u32 s101, 0
	s_cbranch_scc1 .Lrel_skip_0
	s_and_saveexec_b64 s[10:11], vcc
	s_cbranch_execz .LBB0_384
	s_bcnt1_i32_b64 s3, s[8:9]
	v_mov_b32_e32 v0, 0x2000
	v_mov_b32_e32 v1, s3
	global_atomic_add v0, v1, s[6:7] offset:1024
.LBB0_384:
	s_or_b64 exec, exec, s[10:11]
.Lrel_skip_0:
	s_waitcnt vmcnt(0)
.LBB0_385:
	s_or_b64 exec, exec, s[4:5]
	s_waitcnt lgkmcnt(0)
	s_barrier

; __device__ __forceinline__ unsigned xb_ld(unsigned* p)              { return __hip_atomic_load(p, __ATOMIC_RELAXED, __HIP_MEMORY_SCOPE_AGENT); }
; #define XB_SPIN(cond, bar) do { unsigned _sp = 0; while (cond) { __builtin_amdgcn_s_sleep(1); \
;     if ((++_sp & 255u) == 0u) { if (xb_ld(&(bar)[XB_TMO])) break; if (_sp > XB_SPIN_CAP) { atomicAdd(&(bar)[XB_TMO], 1u); break; } } } } while (0)
; __device__ __forceinline__ void xcd_barrier(const XcdBarrier& b) {
;     ...
;             asm volatile("s_waitcnt vmcnt(0)" ::: "memory");
;         } else {
;             XB_SPIN(xb_ld(&bar[XB_XGEN(b.x)]) == gen, bar);
;             __builtin_amdgcn_fence(__ATOMIC_ACQUIRE, "agent");
;             asm volatile("s_waitcnt vmcnt(0)" ::: "memory");
;         }
;     }
;     __syncthreads();
.LBB0_780:
	s_or_b64 exec, exec, s[10:11]
.Lrel_skip_1:
	s_waitcnt vmcnt(0)
.LBB0_781:
	s_or_b64 exec, exec, s[0:1]
	s_waitcnt lgkmcnt(0)
	s_barrier

; __device__ __forceinline__ unsigned xb_ld(unsigned* p)              { return __hip_atomic_load(p, __ATOMIC_RELAXED, __HIP_MEMORY_SCOPE_AGENT); }
; #define XB_SPIN(cond, bar) do { unsigned _sp = 0; while (cond) { __builtin_amdgcn_s_sleep(1); \
;     if ((++_sp & 255u) == 0u) { if (xb_ld(&(bar)[XB_TMO])) break; if (_sp > XB_SPIN_CAP) { atomicAdd(&(bar)[XB_TMO], 1u); break; } } } } while (0)
; __device__ __forceinline__ void xcd_barrier(const XcdBarrier& b) {
;     ...
;             asm volatile("s_waitcnt vmcnt(0)" ::: "memory");
;         } else {
;             XB_SPIN(xb_ld(&bar[XB_XGEN(b.x)]) == gen, bar);
;             __builtin_amdgcn_fence(__ATOMIC_ACQUIRE, "agent");
;             asm volatile("s_waitcnt vmcnt(0)" ::: "memory");
;         }
;     }
;     __syncthreads();
.LBB0_1160:
	s_or_b64 exec, exec, s[10:11]
.Lrel_skip_2:
	s_waitcnt vmcnt(0)
.LBB0_1161:
	s_or_b64 exec, exec, s[4:5]
	s_waitcnt lgkmcnt(0)
	s_barrier

; __device__ __forceinline__ unsigned xb_ld(unsigned* p)              { return __hip_atomic_load(p, __ATOMIC_RELAXED, __HIP_MEMORY_SCOPE_AGENT); }
; #define XB_SPIN(cond, bar) do { unsigned _sp = 0; while (cond) { __builtin_amdgcn_s_sleep(1); \
;     if ((++_sp & 255u) == 0u) { if (xb_ld(&(bar)[XB_TMO])) break; if (_sp > XB_SPIN_CAP) { atomicAdd(&(bar)[XB_TMO], 1u); break; } } } } while (0)
; __device__ __forceinline__ void xcd_barrier(const XcdBarrier& b) {
;     ...
;             asm volatile("s_waitcnt vmcnt(0)" ::: "memory");
;         } else {
;             XB_SPIN(xb_ld(&bar[XB_XGEN(b.x)]) == gen, bar);
;             __builtin_amdgcn_fence(__ATOMIC_ACQUIRE, "agent");
;             asm volatile("s_waitcnt vmcnt(0)" ::: "memory");
;         }
;     }
;     __syncthreads();
.LBB0_1710:
	s_or_b64 exec, exec, s[10:11]
.Lrel_skip_3:
	s_waitcnt vmcnt(0)
.LBB0_1711:
	s_or_b64 exec, exec, s[0:1]
	s_waitcnt lgkmcnt(0)
	s_barrier
